# QK epilogue: q/k norm gains staged into LDS by LDS-DMA at the unit header and read with ds_read_b128; the epilogue's s_waitcnt vmcnt(0) is gone
# speedup vs baseline: 1.0028x; 1.0028x over previous
;     __host__ __device__ bool next(int i, Unit& u) const {
;         const long L = (long)i * G + c; if (L >= nwg) return false;
;         int wgid = (int)L; { const int q = nwg / NXCD, r = nwg % NXCD, xcd = wgid % NXCD, off = wgid / NXCD; wgid = (xcd < r ? xcd * (q + 1) : r * (q + 1) + (xcd - r) * q) + off; }
;         const int nig = WGM * nN, gid = wgid / nig, fm = gid * WGM, gsz = (nM - fm) < WGM ? (nM - fm) : WGM;
;         u.pm = fm + ((wgid % nig) % gsz); u.pn = (wgid % nig) / gsz; return true;
; template <class Epi, class Sched>
; __device__ __forceinline__ void gemm_phase(LAS unsigned char* lds, const Gemm g, const Sched& S, const Epi& E) {
;     ...
;         const bool has_next = S.next(ui + 1, nxt);
.LBB0_342:
	v_readlane_b32 s12, v249, 48
	v_readlane_b32 s13, v249, 49
	v_readlane_b32 s100, v249, 50
	v_readlane_b32 s101, v249, 51
	s_mov_b64 s[98:99], exec
	s_mov_b64 exec, 0xffff
	v_mbcnt_lo_u32_b32 v152, -1, 0
	v_lshlrev_b32_e32 v152, 4, v152
	s_mov_b32 m0, 0x24000
	s_nop 4
	global_load_lds_dwordx4 v152, s[12:13]
	s_mov_b32 m0, 0x24100
	s_nop 0
	global_load_lds_dwordx4 v152, s[100:101]
	s_mov_b64 exec, s[98:99]
	s_add_i32 s40, s43, 1
	s_mul_i32 s48, s40, s39
	s_mul_hi_u32 s49, s40, s56
	s_add_i32 s49, s49, s48
	s_mul_i32 s48, s40, s56
	s_add_u32 s72, s48, s2
	s_addc_u32 s73, s49, s3
	v_cmp_gt_i64_e32 vcc, s[72:73], v[188:189]
	v_cmp_lt_i64_e64 s[66:67], s[72:73], v[180:181]
	s_cbranch_vccnz .LBB0_348
	s_ashr_i32 s48, s72, 31
	s_lshr_b32 s48, s48, 29
	s_add_i32 s48, s72, s48
	s_and_b32 s49, s48, -8
	s_sub_i32 s49, s72, s49
	s_cmp_gt_i32 s49, -1
	s_mov_b64 s[68:69], -1
	s_cbranch_scc0 .LBB0_345
	s_lshl_b32 s53, s49, 7
	s_mov_b64 s[68:69], 0

;     __device__ __forceinline__ void operator()(const f32x4 (&acc)[2][2][4][2], const pg8::Unit& u, int ui, int wr, int wc, int fr, int fq) const {
;         const bool isq = u.pn < 4; bf16_t* dst = isq ? Q : Kb; const float* nw = isq ? qn : kn; const float sc = isq ? 0.125f * LOG2E : 1.f;
;         const int head = (u.pn & 3) * 4 + wc;
;         f32x4 w[2][2];
; #pragma unroll
;         for (int bj = 0; bj < 2; ++bj)
; #pragma unroll
;             for (int n = 0; n < 2; ++n) w[bj][n] = *(const f32x4*)(nw + 32 * bj + 8 * fq + 4 * n) * sc;
; #pragma unroll
;         for (int ai = 0; ai < 2; ++ai)
; #pragma unroll
;             for (int m = 0; m < 4; ++m) {
;                 const int rl = ai * 128 + wr * 64 + m * 16 + fr;
;                 const float r = rs[ui * 256 + rl];
;                 f32x4 v[2][2]; float ss = 0.f;
; #pragma unroll
;                 for (int bj = 0; bj < 2; ++bj)
; #pragma unroll
;                     for (int n = 0; n < 2; ++n) { v[bj][n] = acc[ai][bj][m][n] * r; const f32x4 x = v[bj][n]; ss += (x[0] * x[0] + x[1] * x[1]) + (x[2] * x[2] + x[3] * x[3]); }
;                 ss += __shfl_xor(ss, 16); ss += __shfl_xor(ss, 32);
.LBB0_352:
	s_mov_b32 s19, 0x24100
	s_cmp_lt_i32 s42, 4
	s_cselect_b64 vcc, -1, 0
	s_cselect_b32 s18, 0x24000, s19
	v_lshl_add_u32 v149, v138, 2, s18
	ds_read_b128 v[152:155], v149
	ds_read_b128 v[156:159], v149 offset:16
	ds_read_b128 v[160:163], v149 offset:128
	ds_read_b128 v[164:167], v149 offset:144
	v_lshl_add_u32 v151, s43, 10, v147
	ds_read2_b32 v[170:171], v151 offset1:16
	v_and_b32_e32 v150, 64, v214
	v_xor_b32_e32 v149, 16, v214
	v_add_u32_e32 v150, 64, v150
	v_cndmask_b32_e32 v168, 1.0, v215, vcc
	v_xor_b32_e32 v169, 32, v214
	v_cmp_lt_i32_e32 vcc, v149, v150
	s_waitcnt lgkmcnt(0)
	v_pk_mul_f32 v[126:127], v[126:127], v[170:171] op_sel_hi:[1,0]
	v_pk_mul_f32 v[128:129], v[128:129], v[170:171] op_sel_hi:[1,0]
	v_pk_mul_f32 v[122:123], v[122:123], v[170:171] op_sel_hi:[1,0]
	v_pk_mul_f32 v[124:125], v[124:125], v[170:171] op_sel_hi:[1,0]
	v_pk_mul_f32 v[172:173], v[120:121], v[170:171] op_sel_hi:[1,0]
	v_pk_mul_f32 v[190:191], v[118:119], v[170:171] op_sel_hi:[1,0]
	v_mov_b32_e32 v120, v171
	v_cndmask_b32_e32 v149, v214, v149, vcc
	v_cmp_lt_i32_e32 vcc, v169, v150
	v_pk_mul_f32 v[192:193], v[116:117], v[170:171] op_sel_hi:[1,0]
	v_pk_mul_f32 v[194:195], v[114:115], v[170:171] op_sel_hi:[1,0]
	v_pk_mul_f32 v[114:115], v[128:129], v[128:129]
	v_pk_mul_f32 v[116:117], v[126:127], v[126:127]
	v_pk_mul_f32 v[118:119], v[124:125], v[124:125]
	v_pk_mul_f32 v[170:171], v[122:123], v[122:123]
	v_mul_f32_e32 v196, v190, v190
	v_pk_mul_f32 v[200:201], v[110:111], v[120:121] op_sel_hi:[1,0]
	v_pk_mul_f32 v[202:203], v[112:113], v[120:121] op_sel_hi:[1,0]
	v_pk_mul_f32 v[204:205], v[106:107], v[120:121] op_sel_hi:[1,0]
	v_pk_mul_f32 v[206:207], v[108:109], v[120:121] op_sel_hi:[1,0]
	v_cndmask_b32_e32 v169, v214, v169, vcc
	v_mul_f32_e32 v198, v172, v172
	v_pk_mul_f32 v[208:209], v[104:105], v[120:121] op_sel_hi:[1,0]
	v_pk_mov_b32 v[104:105], v[116:117], v[114:115] op_sel:[1,0]
	v_mov_b32_e32 v117, v115
	v_pk_mov_b32 v[106:107], v[170:171], v[118:119] op_sel:[1,0]
	v_mov_b32_e32 v171, v119
	v_pk_fma_f32 v[108:109], v[190:191], v[190:191], v[196:197] op_sel_hi:[1,1,0]
	v_pk_mul_f32 v[112:113], v[202:203], v[202:203]
	v_pk_mul_f32 v[114:115], v[200:201], v[200:201]
	v_pk_mul_f32 v[118:119], v[206:207], v[206:207]
	v_pk_mul_f32 v[196:197], v[204:205], v[204:205]
	v_pk_mul_f32 v[102:103], v[102:103], v[120:121] op_sel_hi:[1,0]
	v_pk_fma_f32 v[110:111], v[172:173], v[172:173], v[198:199] op_sel_hi:[1,1,0]
	v_pk_add_f32 v[104:105], v[104:105], v[116:117]
	v_pk_mov_b32 v[116:117], v[114:115], v[112:113] op_sel:[1,0]
	v_mov_b32_e32 v115, v113
	v_pk_mov_b32 v[112:113], v[196:197], v[118:119] op_sel:[1,0]
	v_mov_b32_e32 v197, v119
	v_mul_f32_e32 v108, v194, v194
	v_mul_f32_e32 v110, v195, v195
	v_pk_add_f32 v[106:107], v[106:107], v[170:171]
	v_pk_add_f32 v[108:109], v[108:109], v[110:111]
	v_pk_add_f32 v[110:111], v[116:117], v[114:115]
	v_pk_add_f32 v[112:113], v[112:113], v[196:197]
	v_pk_add_f32 v[104:105], v[104:105], v[104:105] op_sel_hi:[0,1]
	v_pk_add_f32 v[106:107], v[106:107], v[106:107] op_sel_hi:[0,1]
	v_pk_add_f32 v[170:171], v[110:111], v[110:111] op_sel_hi:[0,1]
	v_pk_add_f32 v[196:197], v[112:113], v[112:113] op_sel_hi:[0,1]
	v_mul_f32_e32 v104, v192, v192
	v_mul_f32_e32 v106, v193, v193
	v_pk_add_f32 v[104:105], v[104:105], v[106:107]
	v_lshlrev_b32_e32 v150, 2, v149
	v_pk_add_f32 v[198:199], v[108:109], v[104:105]
	v_readlane_b32 s12, v252, 51
	v_readlane_b32 s13, v252, 52
	s_cselect_b32 s19, s65, s13
	s_cselect_b32 s20, s64, s12
	s_lshl_b32 s18, s42, 2
	v_lshlrev_b32_e32 v149, 2, v169
	s_and_b32 s18, s18, 12
	s_or_b32 s21, s18, s35
	s_lshl_b32 s18, s41, 8
	s_lshl_b32 s21, s21, 7
	s_add_u32 s20, s20, s21
	s_addc_u32 s21, s19, 0
	s_mov_b32 s12, 0x3c800000
	v_pk_mul_f32 v[118:119], v[168:169], v[152:153] op_sel_hi:[0,1]
	v_mul_f32_e32 v152, v102, v102
	v_pk_fma_f32 v[152:153], v[102:103], v[102:103], v[152:153] op_sel_hi:[1,1,0]
	v_pk_mul_f32 v[116:117], v[168:169], v[154:155] op_sel_hi:[0,1]
	v_mul_f32_e32 v152, v208, v208
	v_pk_mul_f32 v[112:113], v[168:169], v[158:159] op_sel_hi:[0,1]
	v_pk_mul_f32 v[114:115], v[168:169], v[156:157] op_sel_hi:[0,1]
	v_pk_fma_f32 v[154:155], v[208:209], v[208:209], v[152:153] op_sel_hi:[1,1,0]
	v_pk_mul_f32 v[156:157], v[100:101], v[120:121] op_sel_hi:[1,0]
	v_pk_mul_f32 v[158:159], v[98:99], v[120:121] op_sel_hi:[1,0]
	v_mul_f32_e32 v170, v156, v156
	v_mul_f32_e32 v152, v158, v158
	v_mul_f32_e32 v154, v159, v159
	v_mul_f32_e32 v196, v157, v157
	v_pk_add_f32 v[98:99], v[152:153], v[154:155]
	v_pk_add_f32 v[100:101], v[170:171], v[196:197]
	v_add_u32_e32 v152, s18, v1
	v_pk_add_f32 v[98:99], v[98:99], v[100:101]
	v_mov_b32_e32 v101, v198
	v_mov_b32_e32 v100, v98
	v_mov_b32_e32 v198, v99
	v_pk_add_f32 v[98:99], v[100:101], v[198:199]
	ds_bpermute_b32 v101, v150, v99
	ds_bpermute_b32 v100, v150, v98
	v_ashrrev_i32_e32 v153, 31, v152
	v_pk_mul_f32 v[110:111], v[168:169], v[160:161] op_sel_hi:[0,1]
	v_pk_mul_f32 v[108:109], v[168:169], v[162:163] op_sel_hi:[0,1]
	v_pk_mul_f32 v[104:105], v[168:169], v[166:167] op_sel_hi:[0,1]
	s_waitcnt lgkmcnt(0)
	v_pk_add_f32 v[100:101], v[98:99], v[100:101]
	ds_bpermute_b32 v121, v149, v101
	ds_bpermute_b32 v120, v149, v100
	v_lshlrev_b32_e32 v98, 1, v138
	v_mov_b32_e32 v99, v0
	v_lshl_add_u64 v[98:99], s[20:21], 0, v[98:99]
	s_mov_b32 s20, 0x358637bd
	s_waitcnt lgkmcnt(0)
; __device__ __forceinline__ unsigned cvt_pk_bf16(float lo, float hi) { const f32x2 v = {lo, hi}; const bf16x2_t b = __builtin_convertvector(v, bf16x2_t); return __builtin_bit_cast(unsigned, b); }
;     __device__ __forceinline__ void operator()(const f32x4 (&acc)[2][2][4][2], const pg8::Unit& u, int ui, int wr, int wc, int fr, int fq) const {
;     ...
;                 const int rl = ai * 128 + wr * 64 + m * 16 + fr;
;                 const float r = rs[ui * 256 + rl];
;                 f32x4 v[2][2]; float ss = 0.f;
; #pragma unroll
;                 for (int bj = 0; bj < 2; ++bj)
; #pragma unroll
;                     for (int n = 0; n < 2; ++n) { v[bj][n] = acc[ai][bj][m][n] * r; const f32x4 x = v[bj][n]; ss += (x[0] * x[0] + x[1] * x[1]) + (x[2] * x[2] + x[3] * x[3]); }
;                 ss += __shfl_xor(ss, 16); ss += __shfl_xor(ss, 32);
;                 const float inv = rsqrtf(ss * (1.f / 64.f) + EPS);
; #pragma unroll
;                 for (int bj = 0; bj < 2; ++bj) {
;                     const f32x4 o0 = v[bj][0] * inv * w[bj][0], o1 = v[bj][1] * inv * w[bj][1];
;                     u32x4 pk; pk.x = cvt_pk_bf16(o0[0], o0[1]); pk.y = cvt_pk_bf16(o0[2], o0[3]); pk.z = cvt_pk_bf16(o1[0], o1[1]); pk.w = cvt_pk_bf16(o1[2], o1[3]);
;                     *(u32x4*)(dst + (size_t)(u.pm * 256 + rl) * D + head * 64 + 32 * bj + 8 * fq) = pk;
;                 }
;             }
	v_pk_add_f32 v[120:121], v[100:101], v[120:121]
	v_mov_b64_e32 v[100:101], s[20:21]
	v_pk_fma_f32 v[154:155], v[120:121], s[12:13], v[100:101] op_sel_hi:[1,0,0]
	v_pk_mul_f32 v[106:107], v[168:169], v[164:165] op_sel_hi:[0,1]
	v_mul_f32_e32 v120, 0x4b800000, v155
	v_cmp_gt_f32_e32 vcc, s33, v155
	s_nop 1
	v_cndmask_b32_e32 v120, v155, v120, vcc
	v_rsq_f32_e32 v155, v120
	v_lshlrev_b64 v[120:121], 11, v[152:153]
	v_lshl_add_u64 v[152:153], v[98:99], 0, v[120:121]
	v_mul_f32_e32 v120, 0x45800000, v155
	v_cndmask_b32_e32 v160, v155, v120, vcc
	v_pk_mul_f32 v[120:121], v[126:127], v[160:161] op_sel_hi:[1,0]
	v_pk_mul_f32 v[126:127], v[128:129], v[160:161] op_sel_hi:[1,0]
	v_pk_mul_f32 v[122:123], v[122:123], v[160:161] op_sel_hi:[1,0]
	v_pk_mul_f32 v[124:125], v[124:125], v[160:161] op_sel_hi:[1,0]
	v_pk_mul_f32 v[126:127], v[116:117], v[126:127]
	v_pk_mul_f32 v[120:121], v[118:119], v[120:121]
	v_pk_mul_f32 v[124:125], v[112:113], v[124:125]
	v_pk_mul_f32 v[122:123], v[114:115], v[122:123]
	v_cvt_pk_bf16_f32 v120, v120, v121
	v_cvt_pk_bf16_f32 v121, v126, v127
	v_cvt_pk_bf16_f32 v122, v122, v123
	v_cvt_pk_bf16_f32 v123, v124, v125
	global_store_dwordx4 v[152:153], v[120:123], off
	v_cmp_gt_f32_e32 vcc, s33, v154
	v_pk_mul_f32 v[124:125], v[194:195], v[160:161] op_sel_hi:[1,0]
	v_pk_mul_f32 v[120:121], v[190:191], v[160:161] op_sel_hi:[1,0]
	v_pk_mul_f32 v[122:123], v[172:173], v[160:161] op_sel_hi:[1,0]
	v_pk_mul_f32 v[120:121], v[110:111], v[120:121]
	v_pk_mul_f32 v[122:123], v[108:109], v[122:123]
	v_cvt_pk_bf16_f32 v120, v120, v121
	v_cvt_pk_bf16_f32 v121, v122, v123
	v_mul_f32_e32 v122, 0x4b800000, v154
	v_cndmask_b32_e32 v122, v154, v122, vcc
	v_rsq_f32_e32 v128, v122
	v_pk_mul_f32 v[126:127], v[192:193], v[160:161] op_sel_hi:[1,0]
	v_pk_mul_f32 v[124:125], v[106:107], v[124:125]
	v_pk_mul_f32 v[126:127], v[104:105], v[126:127]
	v_cvt_pk_bf16_f32 v122, v124, v125
	v_cvt_pk_bf16_f32 v123, v126, v127
	global_store_dwordx4 v[152:153], v[120:123], off offset:64
	s_nop 1
	v_mul_f32_e32 v120, 0x45800000, v128
	v_cndmask_b32_e32 v124, v128, v120, vcc
	v_add_u32_e32 v120, s18, v140
	v_ashrrev_i32_e32 v121, 31, v120
	v_lshlrev_b64 v[120:121], 11, v[120:121]
	v_lshl_add_u64 v[126:127], v[98:99], 0, v[120:121]
	v_pk_mul_f32 v[120:121], v[200:201], v[124:125] op_sel_hi:[1,0]
	v_pk_mul_f32 v[122:123], v[202:203], v[124:125] op_sel_hi:[1,0]
	v_pk_mul_f32 v[128:129], v[204:205], v[124:125] op_sel_hi:[1,0]
	v_pk_mul_f32 v[152:153], v[206:207], v[124:125] op_sel_hi:[1,0]
	v_pk_mul_f32 v[122:123], v[116:117], v[122:123]
	v_pk_mul_f32 v[120:121], v[118:119], v[120:121]
	v_pk_mul_f32 v[152:153], v[112:113], v[152:153]
	v_pk_mul_f32 v[128:129], v[114:115], v[128:129]
	v_cvt_pk_bf16_f32 v120, v120, v121
	v_cvt_pk_bf16_f32 v121, v122, v123
	v_cvt_pk_bf16_f32 v122, v128, v129
	v_cvt_pk_bf16_f32 v123, v152, v153
	global_store_dwordx4 v[126:127], v[120:123], off
	ds_read2_b32 v[122:123], v151 offset0:32 offset1:48
	v_pk_mul_f32 v[102:103], v[102:103], v[124:125] op_sel_hi:[1,0]
	v_pk_mul_f32 v[120:121], v[208:209], v[124:125] op_sel_hi:[1,0]
	v_pk_mul_f32 v[128:129], v[158:159], v[124:125] op_sel_hi:[1,0]
	v_pk_mul_f32 v[124:125], v[156:157], v[124:125] op_sel_hi:[1,0]
	s_waitcnt lgkmcnt(0)
	v_pk_mul_f32 v[94:95], v[94:95], v[122:123] op_sel_hi:[1,0]
	v_pk_mul_f32 v[96:97], v[96:97], v[122:123] op_sel_hi:[1,0]
	v_pk_mul_f32 v[154:155], v[94:95], v[94:95]
	v_pk_mul_f32 v[152:153], v[96:97], v[96:97]
	v_pk_mul_f32 v[90:91], v[90:91], v[122:123] op_sel_hi:[1,0]
	v_pk_mov_b32 v[156:157], v[154:155], v[152:153] op_sel:[1,0]
	v_mov_b32_e32 v155, v153
	v_pk_add_f32 v[152:153], v[156:157], v[154:155]
	v_pk_mul_f32 v[92:93], v[92:93], v[122:123] op_sel_hi:[1,0]
	v_pk_add_f32 v[152:153], v[152:153], v[152:153] op_sel_hi:[0,1]
	v_pk_mul_f32 v[154:155], v[92:93], v[92:93]
	v_pk_mul_f32 v[156:157], v[90:91], v[90:91]
	v_pk_mul_f32 v[86:87], v[86:87], v[122:123] op_sel_hi:[1,0]
	v_pk_mov_b32 v[158:159], v[156:157], v[154:155] op_sel:[1,0]
	v_mov_b32_e32 v157, v155
	v_pk_mul_f32 v[88:89], v[88:89], v[122:123] op_sel_hi:[1,0]
	v_mul_f32_e32 v152, v86, v86
	v_pk_add_f32 v[154:155], v[158:159], v[156:157]
	v_pk_fma_f32 v[156:157], v[86:87], v[86:87], v[152:153] op_sel_hi:[1,1,0]
	v_mul_f32_e32 v152, v88, v88
	v_pk_add_f32 v[154:155], v[154:155], v[154:155] op_sel_hi:[0,1]
	v_pk_fma_f32 v[158:159], v[88:89], v[88:89], v[152:153] op_sel_hi:[1,1,0]
	v_pk_mul_f32 v[80:81], v[80:81], v[122:123] op_sel_hi:[1,0]
	v_pk_mul_f32 v[78:79], v[78:79], v[122:123] op_sel_hi:[1,0]
	v_mul_f32_e32 v152, v80, v80
	v_mul_f32_e32 v156, v78, v78
	v_mul_f32_e32 v158, v79, v79
	v_mul_f32_e32 v154, v81, v81
	v_mov_b32_e32 v122, v123
	v_pk_add_f32 v[156:157], v[156:157], v[158:159]
	v_pk_add_f32 v[152:153], v[152:153], v[154:155]
	v_pk_mul_f32 v[82:83], v[82:83], v[122:123] op_sel_hi:[1,0]
	v_pk_mul_f32 v[84:85], v[84:85], v[122:123] op_sel_hi:[1,0]
	v_pk_add_f32 v[152:153], v[156:157], v[152:153]
	v_pk_mul_f32 v[154:155], v[84:85], v[84:85]
	v_pk_mul_f32 v[156:157], v[82:83], v[82:83]
	v_pk_mul_f32 v[74:75], v[74:75], v[122:123] op_sel_hi:[1,0]
	v_pk_mov_b32 v[158:159], v[156:157], v[154:155] op_sel:[1,0]
	v_mov_b32_e32 v157, v155
	v_pk_add_f32 v[154:155], v[158:159], v[156:157]
	v_pk_mul_f32 v[76:77], v[76:77], v[122:123] op_sel_hi:[1,0]
	v_pk_add_f32 v[154:155], v[154:155], v[154:155] op_sel_hi:[0,1]
	v_pk_mul_f32 v[156:157], v[76:77], v[76:77]
	v_pk_mul_f32 v[158:159], v[74:75], v[74:75]
	v_pk_mul_f32 v[70:71], v[70:71], v[122:123] op_sel_hi:[1,0]
	v_pk_mov_b32 v[160:161], v[158:159], v[156:157] op_sel:[1,0]
	v_mov_b32_e32 v159, v157
	v_pk_mul_f32 v[72:73], v[72:73], v[122:123] op_sel_hi:[1,0]
	v_mul_f32_e32 v154, v70, v70
	v_pk_add_f32 v[156:157], v[160:161], v[158:159]
	v_pk_fma_f32 v[158:159], v[70:71], v[70:71], v[154:155] op_sel_hi:[1,1,0]
	v_mul_f32_e32 v154, v72, v72
	v_pk_add_f32 v[156:157], v[156:157], v[156:157] op_sel_hi:[0,1]
	v_pk_fma_f32 v[160:161], v[72:73], v[72:73], v[154:155] op_sel_hi:[1,1,0]
	v_pk_mul_f32 v[162:163], v[68:69], v[122:123] op_sel_hi:[1,0]
	v_pk_mul_f32 v[122:123], v[66:67], v[122:123] op_sel_hi:[1,0]
	v_mul_f32_e32 v154, v162, v162
	v_mul_f32_e32 v158, v122, v122
	v_mul_f32_e32 v160, v123, v123
	v_mul_f32_e32 v156, v163, v163
	v_pk_add_f32 v[66:67], v[158:159], v[160:161]
	v_pk_add_f32 v[68:69], v[154:155], v[156:157]
	v_pk_mul_f32 v[102:103], v[110:111], v[102:103]
	v_pk_add_f32 v[66:67], v[66:67], v[68:69]
	v_mov_b32_e32 v69, v152
	v_mov_b32_e32 v68, v66
	v_mov_b32_e32 v152, v67
	v_pk_add_f32 v[68:69], v[68:69], v[152:153]
	ds_bpermute_b32 v153, v150, v69
	ds_bpermute_b32 v152, v150, v68
	v_pk_mul_f32 v[120:121], v[108:109], v[120:121]
	v_cvt_pk_bf16_f32 v66, v102, v103
	v_cvt_pk_bf16_f32 v67, v120, v121
	v_pk_mul_f32 v[124:125], v[104:105], v[124:125]
	s_waitcnt lgkmcnt(0)
; __device__ __forceinline__ unsigned cvt_pk_bf16(float lo, float hi) { const f32x2 v = {lo, hi}; const bf16x2_t b = __builtin_convertvector(v, bf16x2_t); return __builtin_bit_cast(unsigned, b); }
;     __device__ __forceinline__ void operator()(const f32x4 (&acc)[2][2][4][2], const pg8::Unit& u, int ui, int wr, int wc, int fr, int fq) const {
;     ...
;                 const int rl = ai * 128 + wr * 64 + m * 16 + fr;
;                 const float r = rs[ui * 256 + rl];
;                 f32x4 v[2][2]; float ss = 0.f;
; #pragma unroll
;                 for (int bj = 0; bj < 2; ++bj)
; #pragma unroll
;                     for (int n = 0; n < 2; ++n) { v[bj][n] = acc[ai][bj][m][n] * r; const f32x4 x = v[bj][n]; ss += (x[0] * x[0] + x[1] * x[1]) + (x[2] * x[2] + x[3] * x[3]); }
;                 ss += __shfl_xor(ss, 16); ss += __shfl_xor(ss, 32);
;                 const float inv = rsqrtf(ss * (1.f / 64.f) + EPS);
; #pragma unroll
;                 for (int bj = 0; bj < 2; ++bj) {
;                     const f32x4 o0 = v[bj][0] * inv * w[bj][0], o1 = v[bj][1] * inv * w[bj][1];
;                     u32x4 pk; pk.x = cvt_pk_bf16(o0[0], o0[1]); pk.y = cvt_pk_bf16(o0[2], o0[3]); pk.z = cvt_pk_bf16(o1[0], o1[1]); pk.w = cvt_pk_bf16(o1[2], o1[3]);
;                     *(u32x4*)(dst + (size_t)(u.pm * 256 + rl) * D + head * 64 + 32 * bj + 8 * fq) = pk;
;                 }
;             }
	v_pk_add_f32 v[102:103], v[68:69], v[152:153]
	ds_bpermute_b32 v121, v149, v103
	ds_bpermute_b32 v120, v149, v102
	v_pk_mul_f32 v[128:129], v[106:107], v[128:129]
	v_cvt_pk_bf16_f32 v69, v124, v125
	v_cvt_pk_bf16_f32 v68, v128, v129
	global_store_dwordx4 v[126:127], v[66:69], off offset:64
	s_waitcnt lgkmcnt(0)
	s_nop 0
	v_pk_add_f32 v[68:69], v[102:103], v[120:121]
	v_add_u32_e32 v66, s18, v141
	v_pk_fma_f32 v[102:103], v[68:69], s[12:13], v[100:101] op_sel_hi:[1,0,0]
	s_nop 0
	v_mul_f32_e32 v67, 0x4b800000, v103
	v_cmp_gt_f32_e32 vcc, s33, v103
	s_nop 1
	v_cndmask_b32_e32 v67, v103, v67, vcc
	v_rsq_f32_e32 v68, v67
	v_ashrrev_i32_e32 v67, 31, v66
	v_lshlrev_b64 v[66:67], 11, v[66:67]
	v_lshl_add_u64 v[120:121], v[98:99], 0, v[66:67]
	v_mul_f32_e32 v66, 0x45800000, v68
	v_cndmask_b32_e32 v124, v68, v66, vcc
	v_pk_mul_f32 v[66:67], v[94:95], v[124:125] op_sel_hi:[1,0]
	v_pk_mul_f32 v[68:69], v[96:97], v[124:125] op_sel_hi:[1,0]
	v_pk_mul_f32 v[90:91], v[90:91], v[124:125] op_sel_hi:[1,0]
	v_pk_mul_f32 v[92:93], v[92:93], v[124:125] op_sel_hi:[1,0]
	v_pk_mul_f32 v[68:69], v[116:117], v[68:69]
	v_pk_mul_f32 v[66:67], v[118:119], v[66:67]
	v_pk_mul_f32 v[92:93], v[112:113], v[92:93]
	v_pk_mul_f32 v[90:91], v[114:115], v[90:91]
	v_cvt_pk_bf16_f32 v66, v66, v67
	v_cvt_pk_bf16_f32 v67, v68, v69
	v_cvt_pk_bf16_f32 v68, v90, v91
	v_cvt_pk_bf16_f32 v69, v92, v93
	global_store_dwordx4 v[120:121], v[66:69], off
	v_cmp_gt_f32_e32 vcc, s33, v102
	v_pk_mul_f32 v[78:79], v[78:79], v[124:125] op_sel_hi:[1,0]
	v_pk_mul_f32 v[66:67], v[86:87], v[124:125] op_sel_hi:[1,0]
	v_pk_mul_f32 v[68:69], v[88:89], v[124:125] op_sel_hi:[1,0]
	v_pk_mul_f32 v[66:67], v[110:111], v[66:67]
	v_pk_mul_f32 v[68:69], v[108:109], v[68:69]
	v_cvt_pk_bf16_f32 v66, v66, v67
	v_cvt_pk_bf16_f32 v67, v68, v69
	v_mul_f32_e32 v68, 0x4b800000, v102
	v_cndmask_b32_e32 v68, v102, v68, vcc
	v_rsq_f32_e32 v86, v68
	v_pk_mul_f32 v[80:81], v[80:81], v[124:125] op_sel_hi:[1,0]
	v_pk_mul_f32 v[78:79], v[106:107], v[78:79]
	v_pk_mul_f32 v[80:81], v[104:105], v[80:81]
	v_cvt_pk_bf16_f32 v68, v78, v79
	v_cvt_pk_bf16_f32 v69, v80, v81
	global_store_dwordx4 v[120:121], v[66:69], off offset:64
	s_nop 1
	v_mul_f32_e32 v66, 0x45800000, v86
	v_cndmask_b32_e32 v78, v86, v66, vcc
	v_add_u32_e32 v66, s18, v142
	v_ashrrev_i32_e32 v67, 31, v66
	v_lshlrev_b64 v[66:67], 11, v[66:67]
	v_lshl_add_u64 v[80:81], v[98:99], 0, v[66:67]
	v_pk_mul_f32 v[66:67], v[82:83], v[78:79] op_sel_hi:[1,0]
	v_pk_mul_f32 v[68:69], v[84:85], v[78:79] op_sel_hi:[1,0]
	v_pk_mul_f32 v[74:75], v[74:75], v[78:79] op_sel_hi:[1,0]
	v_pk_mul_f32 v[76:77], v[76:77], v[78:79] op_sel_hi:[1,0]
	v_pk_mul_f32 v[68:69], v[116:117], v[68:69]
	v_pk_mul_f32 v[66:67], v[118:119], v[66:67]
	v_pk_mul_f32 v[76:77], v[112:113], v[76:77]
	v_pk_mul_f32 v[74:75], v[114:115], v[74:75]
	v_cvt_pk_bf16_f32 v66, v66, v67
	v_cvt_pk_bf16_f32 v67, v68, v69
	v_cvt_pk_bf16_f32 v68, v74, v75
	v_cvt_pk_bf16_f32 v69, v76, v77
	global_store_dwordx4 v[80:81], v[66:69], off
	v_pk_mul_f32 v[74:75], v[162:163], v[78:79] op_sel_hi:[1,0]
	s_nop 0
	v_pk_mul_f32 v[66:67], v[70:71], v[78:79] op_sel_hi:[1,0]
	ds_read2_b32 v[70:71], v151 offset0:128 offset1:144
	v_pk_mul_f32 v[68:69], v[72:73], v[78:79] op_sel_hi:[1,0]
	v_pk_mul_f32 v[72:73], v[122:123], v[78:79] op_sel_hi:[1,0]
	v_pk_mul_f32 v[66:67], v[110:111], v[66:67]
	v_pk_mul_f32 v[68:69], v[108:109], v[68:69]
	s_waitcnt lgkmcnt(0)
	v_pk_mul_f32 v[62:63], v[62:63], v[70:71] op_sel_hi:[1,0]
	v_pk_mul_f32 v[64:65], v[64:65], v[70:71] op_sel_hi:[1,0]
	v_pk_mul_f32 v[78:79], v[62:63], v[62:63]
	v_pk_mul_f32 v[76:77], v[64:65], v[64:65]
	v_pk_mul_f32 v[58:59], v[58:59], v[70:71] op_sel_hi:[1,0]
	v_pk_mov_b32 v[82:83], v[78:79], v[76:77] op_sel:[1,0]
	v_mov_b32_e32 v79, v77
	v_pk_add_f32 v[76:77], v[82:83], v[78:79]
	v_pk_mul_f32 v[60:61], v[60:61], v[70:71] op_sel_hi:[1,0]
	v_pk_add_f32 v[76:77], v[76:77], v[76:77] op_sel_hi:[0,1]
	v_pk_mul_f32 v[78:79], v[60:61], v[60:61]
	v_pk_mul_f32 v[82:83], v[58:59], v[58:59]
	v_pk_mul_f32 v[54:55], v[54:55], v[70:71] op_sel_hi:[1,0]
	v_pk_mov_b32 v[84:85], v[82:83], v[78:79] op_sel:[1,0]
	v_mov_b32_e32 v83, v79
	v_pk_mul_f32 v[56:57], v[56:57], v[70:71] op_sel_hi:[1,0]
	v_mul_f32_e32 v76, v54, v54
	v_pk_add_f32 v[78:79], v[84:85], v[82:83]
	v_pk_fma_f32 v[82:83], v[54:55], v[54:55], v[76:77] op_sel_hi:[1,1,0]
	v_mul_f32_e32 v76, v56, v56
	v_pk_add_f32 v[78:79], v[78:79], v[78:79] op_sel_hi:[0,1]
	v_pk_fma_f32 v[84:85], v[56:57], v[56:57], v[76:77] op_sel_hi:[1,1,0]
	v_pk_mul_f32 v[48:49], v[48:49], v[70:71] op_sel_hi:[1,0]
	v_pk_mul_f32 v[46:47], v[46:47], v[70:71] op_sel_hi:[1,0]
	v_mul_f32_e32 v76, v48, v48
	v_mul_f32_e32 v82, v46, v46
	v_mul_f32_e32 v84, v47, v47
	v_mul_f32_e32 v78, v49, v49
	v_mov_b32_e32 v70, v71
	v_pk_add_f32 v[82:83], v[82:83], v[84:85]
	v_pk_add_f32 v[76:77], v[76:77], v[78:79]
	v_pk_mul_f32 v[50:51], v[50:51], v[70:71] op_sel_hi:[1,0]
	v_pk_mul_f32 v[52:53], v[52:53], v[70:71] op_sel_hi:[1,0]
	v_pk_add_f32 v[76:77], v[82:83], v[76:77]
	v_pk_mul_f32 v[78:79], v[52:53], v[52:53]
	v_pk_mul_f32 v[82:83], v[50:51], v[50:51]
	v_pk_mul_f32 v[42:43], v[42:43], v[70:71] op_sel_hi:[1,0]
	v_pk_mov_b32 v[84:85], v[82:83], v[78:79] op_sel:[1,0]
	v_mov_b32_e32 v83, v79
	v_pk_add_f32 v[78:79], v[84:85], v[82:83]
	v_pk_mul_f32 v[44:45], v[44:45], v[70:71] op_sel_hi:[1,0]
	v_pk_add_f32 v[78:79], v[78:79], v[78:79] op_sel_hi:[0,1]
	v_pk_mul_f32 v[82:83], v[44:45], v[44:45]
	v_pk_mul_f32 v[84:85], v[42:43], v[42:43]
	v_pk_mul_f32 v[38:39], v[38:39], v[70:71] op_sel_hi:[1,0]
	v_pk_mov_b32 v[86:87], v[84:85], v[82:83] op_sel:[1,0]
	v_mov_b32_e32 v85, v83
	v_pk_mul_f32 v[40:41], v[40:41], v[70:71] op_sel_hi:[1,0]
	v_mul_f32_e32 v78, v38, v38
	v_pk_add_f32 v[82:83], v[86:87], v[84:85]
	v_pk_fma_f32 v[84:85], v[38:39], v[38:39], v[78:79] op_sel_hi:[1,1,0]
	v_mul_f32_e32 v78, v40, v40
	v_pk_add_f32 v[82:83], v[82:83], v[82:83] op_sel_hi:[0,1]
	v_pk_fma_f32 v[86:87], v[40:41], v[40:41], v[78:79] op_sel_hi:[1,1,0]
	v_pk_mul_f32 v[88:89], v[36:37], v[70:71] op_sel_hi:[1,0]
	v_pk_mul_f32 v[70:71], v[34:35], v[70:71] op_sel_hi:[1,0]
	v_mul_f32_e32 v78, v88, v88
	v_mul_f32_e32 v84, v70, v70
	v_mul_f32_e32 v86, v71, v71
	v_mul_f32_e32 v82, v89, v89
	v_pk_add_f32 v[34:35], v[84:85], v[86:87]
	v_pk_add_f32 v[36:37], v[78:79], v[82:83]
	v_pk_mul_f32 v[74:75], v[104:105], v[74:75]
	v_pk_add_f32 v[34:35], v[34:35], v[36:37]
	v_mov_b32_e32 v37, v76
	v_mov_b32_e32 v36, v34
	v_mov_b32_e32 v76, v35
	v_pk_add_f32 v[36:37], v[36:37], v[76:77]
	ds_bpermute_b32 v77, v150, v37
	ds_bpermute_b32 v76, v150, v36
	v_cvt_pk_bf16_f32 v34, v66, v67
	v_cvt_pk_bf16_f32 v35, v68, v69
	v_pk_mul_f32 v[72:73], v[106:107], v[72:73]
	s_waitcnt lgkmcnt(0)
; __device__ __forceinline__ unsigned cvt_pk_bf16(float lo, float hi) { const f32x2 v = {lo, hi}; const bf16x2_t b = __builtin_convertvector(v, bf16x2_t); return __builtin_bit_cast(unsigned, b); }
;     __device__ __forceinline__ void operator()(const f32x4 (&acc)[2][2][4][2], const pg8::Unit& u, int ui, int wr, int wc, int fr, int fq) const {
;     ...
;                 const int rl = ai * 128 + wr * 64 + m * 16 + fr;
;                 const float r = rs[ui * 256 + rl];
;                 f32x4 v[2][2]; float ss = 0.f;
; #pragma unroll
;                 for (int bj = 0; bj < 2; ++bj)
; #pragma unroll
;                     for (int n = 0; n < 2; ++n) { v[bj][n] = acc[ai][bj][m][n] * r; const f32x4 x = v[bj][n]; ss += (x[0] * x[0] + x[1] * x[1]) + (x[2] * x[2] + x[3] * x[3]); }
;                 ss += __shfl_xor(ss, 16); ss += __shfl_xor(ss, 32);
;                 const float inv = rsqrtf(ss * (1.f / 64.f) + EPS);
; #pragma unroll
;                 for (int bj = 0; bj < 2; ++bj) {
;                     const f32x4 o0 = v[bj][0] * inv * w[bj][0], o1 = v[bj][1] * inv * w[bj][1];
;                     u32x4 pk; pk.x = cvt_pk_bf16(o0[0], o0[1]); pk.y = cvt_pk_bf16(o0[2], o0[3]); pk.z = cvt_pk_bf16(o1[0], o1[1]); pk.w = cvt_pk_bf16(o1[2], o1[3]);
;                     *(u32x4*)(dst + (size_t)(u.pm * 256 + rl) * D + head * 64 + 32 * bj + 8 * fq) = pk;
;                 }
;             }
	v_pk_add_f32 v[66:67], v[36:37], v[76:77]
	ds_bpermute_b32 v69, v149, v67
	ds_bpermute_b32 v68, v149, v66
	v_cvt_pk_bf16_f32 v36, v72, v73
	v_cvt_pk_bf16_f32 v37, v74, v75
	global_store_dwordx4 v[80:81], v[34:37], off offset:64
	s_waitcnt lgkmcnt(0)
	s_nop 0
	v_pk_add_f32 v[36:37], v[66:67], v[68:69]
	v_add_u32_e32 v34, s18, v143
	v_pk_fma_f32 v[66:67], v[36:37], s[12:13], v[100:101] op_sel_hi:[1,0,0]
	s_nop 0
	v_mul_f32_e32 v35, 0x4b800000, v67
	v_cmp_gt_f32_e32 vcc, s33, v67
	s_nop 1
	v_cndmask_b32_e32 v35, v67, v35, vcc
	v_rsq_f32_e32 v36, v35
	v_ashrrev_i32_e32 v35, 31, v34
	v_lshlrev_b64 v[34:35], 11, v[34:35]
	v_lshl_add_u64 v[68:69], v[98:99], 0, v[34:35]
	v_mul_f32_e32 v34, 0x45800000, v36
	v_cndmask_b32_e32 v72, v36, v34, vcc
	v_pk_mul_f32 v[34:35], v[62:63], v[72:73] op_sel_hi:[1,0]
	v_pk_mul_f32 v[36:37], v[64:65], v[72:73] op_sel_hi:[1,0]
	v_pk_mul_f32 v[58:59], v[58:59], v[72:73] op_sel_hi:[1,0]
	v_pk_mul_f32 v[60:61], v[60:61], v[72:73] op_sel_hi:[1,0]
	v_pk_mul_f32 v[36:37], v[116:117], v[36:37]
	v_pk_mul_f32 v[34:35], v[118:119], v[34:35]
	v_pk_mul_f32 v[60:61], v[112:113], v[60:61]
	v_pk_mul_f32 v[58:59], v[114:115], v[58:59]
	v_cvt_pk_bf16_f32 v34, v34, v35
	v_cvt_pk_bf16_f32 v35, v36, v37
	v_cvt_pk_bf16_f32 v36, v58, v59
	v_cvt_pk_bf16_f32 v37, v60, v61
	global_store_dwordx4 v[68:69], v[34:37], off
	v_cmp_gt_f32_e32 vcc, s33, v66
	v_pk_mul_f32 v[46:47], v[46:47], v[72:73] op_sel_hi:[1,0]
	v_pk_mul_f32 v[34:35], v[54:55], v[72:73] op_sel_hi:[1,0]
	v_pk_mul_f32 v[36:37], v[56:57], v[72:73] op_sel_hi:[1,0]
	v_pk_mul_f32 v[34:35], v[110:111], v[34:35]
	v_pk_mul_f32 v[36:37], v[108:109], v[36:37]
	v_cvt_pk_bf16_f32 v34, v34, v35
	v_cvt_pk_bf16_f32 v35, v36, v37
	v_mul_f32_e32 v36, 0x4b800000, v66
	v_cndmask_b32_e32 v36, v66, v36, vcc
	v_rsq_f32_e32 v54, v36
	v_pk_mul_f32 v[48:49], v[48:49], v[72:73] op_sel_hi:[1,0]
	v_pk_mul_f32 v[46:47], v[106:107], v[46:47]
	v_pk_mul_f32 v[48:49], v[104:105], v[48:49]
	v_cvt_pk_bf16_f32 v36, v46, v47
	v_cvt_pk_bf16_f32 v37, v48, v49
	global_store_dwordx4 v[68:69], v[34:37], off offset:64
	s_nop 1
	v_mul_f32_e32 v34, 0x45800000, v54
	v_cndmask_b32_e32 v46, v54, v34, vcc
	v_add_u32_e32 v34, s18, v144
	v_ashrrev_i32_e32 v35, 31, v34
	v_lshlrev_b64 v[34:35], 11, v[34:35]
	v_lshl_add_u64 v[48:49], v[98:99], 0, v[34:35]
	v_pk_mul_f32 v[34:35], v[50:51], v[46:47] op_sel_hi:[1,0]
	v_pk_mul_f32 v[36:37], v[52:53], v[46:47] op_sel_hi:[1,0]
	v_pk_mul_f32 v[42:43], v[42:43], v[46:47] op_sel_hi:[1,0]
	v_pk_mul_f32 v[44:45], v[44:45], v[46:47] op_sel_hi:[1,0]
	v_pk_mul_f32 v[36:37], v[116:117], v[36:37]
	v_pk_mul_f32 v[34:35], v[118:119], v[34:35]
	v_pk_mul_f32 v[44:45], v[112:113], v[44:45]
	v_pk_mul_f32 v[42:43], v[114:115], v[42:43]
	v_cvt_pk_bf16_f32 v34, v34, v35
	v_cvt_pk_bf16_f32 v35, v36, v37
	v_cvt_pk_bf16_f32 v36, v42, v43
	v_cvt_pk_bf16_f32 v37, v44, v45
	global_store_dwordx4 v[48:49], v[34:37], off
	v_pk_mul_f32 v[42:43], v[88:89], v[46:47] op_sel_hi:[1,0]
	s_nop 0
	v_pk_mul_f32 v[34:35], v[38:39], v[46:47] op_sel_hi:[1,0]
	ds_read2_b32 v[38:39], v151 offset0:160 offset1:176
	v_pk_mul_f32 v[36:37], v[40:41], v[46:47] op_sel_hi:[1,0]
	v_pk_mul_f32 v[40:41], v[70:71], v[46:47] op_sel_hi:[1,0]
	v_pk_mul_f32 v[34:35], v[110:111], v[34:35]
	v_pk_mul_f32 v[36:37], v[108:109], v[36:37]
	s_waitcnt lgkmcnt(0)
	v_pk_mul_f32 v[30:31], v[30:31], v[38:39] op_sel_hi:[1,0]
	v_pk_mul_f32 v[32:33], v[32:33], v[38:39] op_sel_hi:[1,0]
	v_pk_mul_f32 v[46:47], v[30:31], v[30:31]
	v_pk_mul_f32 v[44:45], v[32:33], v[32:33]
	v_pk_mul_f32 v[26:27], v[26:27], v[38:39] op_sel_hi:[1,0]
	v_pk_mov_b32 v[50:51], v[46:47], v[44:45] op_sel:[1,0]
	v_mov_b32_e32 v47, v45
	v_pk_add_f32 v[44:45], v[50:51], v[46:47]
	v_pk_mul_f32 v[28:29], v[28:29], v[38:39] op_sel_hi:[1,0]
	v_pk_add_f32 v[44:45], v[44:45], v[44:45] op_sel_hi:[0,1]
	v_pk_mul_f32 v[46:47], v[28:29], v[28:29]
	v_pk_mul_f32 v[50:51], v[26:27], v[26:27]
	v_pk_mul_f32 v[22:23], v[22:23], v[38:39] op_sel_hi:[1,0]
	v_pk_mov_b32 v[52:53], v[50:51], v[46:47] op_sel:[1,0]
	v_mov_b32_e32 v51, v47
	v_pk_mul_f32 v[24:25], v[24:25], v[38:39] op_sel_hi:[1,0]
	v_mul_f32_e32 v44, v22, v22
	v_pk_add_f32 v[46:47], v[52:53], v[50:51]
	v_pk_fma_f32 v[50:51], v[22:23], v[22:23], v[44:45] op_sel_hi:[1,1,0]
	v_mul_f32_e32 v44, v24, v24
	v_pk_add_f32 v[46:47], v[46:47], v[46:47] op_sel_hi:[0,1]
	v_pk_fma_f32 v[52:53], v[24:25], v[24:25], v[44:45] op_sel_hi:[1,1,0]
	v_pk_mul_f32 v[16:17], v[16:17], v[38:39] op_sel_hi:[1,0]
	v_pk_mul_f32 v[14:15], v[14:15], v[38:39] op_sel_hi:[1,0]
	v_mul_f32_e32 v44, v16, v16
	v_mul_f32_e32 v50, v14, v14
	v_mul_f32_e32 v52, v15, v15
	v_mul_f32_e32 v46, v17, v17
	v_mov_b32_e32 v38, v39
	v_pk_add_f32 v[50:51], v[50:51], v[52:53]
	v_pk_add_f32 v[44:45], v[44:45], v[46:47]
	v_pk_mul_f32 v[18:19], v[18:19], v[38:39] op_sel_hi:[1,0]
	v_pk_mul_f32 v[20:21], v[20:21], v[38:39] op_sel_hi:[1,0]
	v_pk_add_f32 v[44:45], v[50:51], v[44:45]
	v_pk_mul_f32 v[46:47], v[20:21], v[20:21]
	v_pk_mul_f32 v[50:51], v[18:19], v[18:19]
	v_pk_mul_f32 v[10:11], v[10:11], v[38:39] op_sel_hi:[1,0]
	v_pk_mov_b32 v[52:53], v[50:51], v[46:47] op_sel:[1,0]
	v_mov_b32_e32 v51, v47
	v_pk_add_f32 v[46:47], v[52:53], v[50:51]
	v_pk_mul_f32 v[12:13], v[12:13], v[38:39] op_sel_hi:[1,0]
	v_pk_add_f32 v[46:47], v[46:47], v[46:47] op_sel_hi:[0,1]
	v_pk_mul_f32 v[50:51], v[12:13], v[12:13]
	v_pk_mul_f32 v[52:53], v[10:11], v[10:11]
	v_pk_mul_f32 v[6:7], v[6:7], v[38:39] op_sel_hi:[1,0]
	v_pk_mov_b32 v[54:55], v[52:53], v[50:51] op_sel:[1,0]
	v_mov_b32_e32 v53, v51
	v_pk_mul_f32 v[8:9], v[8:9], v[38:39] op_sel_hi:[1,0]
	v_mul_f32_e32 v46, v6, v6
	v_pk_add_f32 v[50:51], v[54:55], v[52:53]
	v_pk_fma_f32 v[52:53], v[6:7], v[6:7], v[46:47] op_sel_hi:[1,1,0]
	v_mul_f32_e32 v46, v8, v8
	v_pk_add_f32 v[50:51], v[50:51], v[50:51] op_sel_hi:[0,1]
	v_pk_fma_f32 v[54:55], v[8:9], v[8:9], v[46:47] op_sel_hi:[1,1,0]
	v_pk_mul_f32 v[56:57], v[4:5], v[38:39] op_sel_hi:[1,0]
	v_pk_mul_f32 v[38:39], v[2:3], v[38:39] op_sel_hi:[1,0]
	v_mul_f32_e32 v46, v56, v56
	v_mul_f32_e32 v52, v38, v38
	v_mul_f32_e32 v54, v39, v39
	v_mul_f32_e32 v50, v57, v57
	v_pk_add_f32 v[2:3], v[52:53], v[54:55]
	v_pk_add_f32 v[4:5], v[46:47], v[50:51]
	v_pk_mul_f32 v[42:43], v[104:105], v[42:43]
	v_pk_add_f32 v[2:3], v[2:3], v[4:5]
	v_mov_b32_e32 v5, v44
	v_mov_b32_e32 v4, v2
	v_mov_b32_e32 v44, v3
	v_pk_add_f32 v[4:5], v[4:5], v[44:45]
	ds_bpermute_b32 v45, v150, v5
	ds_bpermute_b32 v44, v150, v4
	v_cvt_pk_bf16_f32 v2, v34, v35
	v_cvt_pk_bf16_f32 v3, v36, v37
	v_pk_mul_f32 v[40:41], v[106:107], v[40:41]
	s_waitcnt lgkmcnt(0)
; __device__ __forceinline__ unsigned cvt_pk_bf16(float lo, float hi) { const f32x2 v = {lo, hi}; const bf16x2_t b = __builtin_convertvector(v, bf16x2_t); return __builtin_bit_cast(unsigned, b); }
;     __device__ __forceinline__ void operator()(const f32x4 (&acc)[2][2][4][2], const pg8::Unit& u, int ui, int wr, int wc, int fr, int fq) const {
;     ...
;                 const int rl = ai * 128 + wr * 64 + m * 16 + fr;
;                 const float r = rs[ui * 256 + rl];
;                 f32x4 v[2][2]; float ss = 0.f;
; #pragma unroll
;                 for (int bj = 0; bj < 2; ++bj)
; #pragma unroll
;                     for (int n = 0; n < 2; ++n) { v[bj][n] = acc[ai][bj][m][n] * r; const f32x4 x = v[bj][n]; ss += (x[0] * x[0] + x[1] * x[1]) + (x[2] * x[2] + x[3] * x[3]); }
;                 ss += __shfl_xor(ss, 16); ss += __shfl_xor(ss, 32);
;                 const float inv = rsqrtf(ss * (1.f / 64.f) + EPS);
; #pragma unroll
;                 for (int bj = 0; bj < 2; ++bj) {
;                     const f32x4 o0 = v[bj][0] * inv * w[bj][0], o1 = v[bj][1] * inv * w[bj][1];
;                     u32x4 pk; pk.x = cvt_pk_bf16(o0[0], o0[1]); pk.y = cvt_pk_bf16(o0[2], o0[3]); pk.z = cvt_pk_bf16(o1[0], o1[1]); pk.w = cvt_pk_bf16(o1[2], o1[3]);
;                     *(u32x4*)(dst + (size_t)(u.pm * 256 + rl) * D + head * 64 + 32 * bj + 8 * fq) = pk;
;                 }
;             }
	v_pk_add_f32 v[34:35], v[4:5], v[44:45]
	ds_bpermute_b32 v37, v149, v35
	ds_bpermute_b32 v36, v149, v34
	v_cvt_pk_bf16_f32 v4, v40, v41
	v_cvt_pk_bf16_f32 v5, v42, v43
	global_store_dwordx4 v[48:49], v[2:5], off offset:64
	s_waitcnt lgkmcnt(0)
	s_nop 0
	v_pk_add_f32 v[4:5], v[34:35], v[36:37]
	v_add_u32_e32 v2, s18, v145
	v_pk_fma_f32 v[34:35], v[4:5], s[12:13], v[100:101] op_sel_hi:[1,0,0]
	s_nop 0
	v_mul_f32_e32 v3, 0x4b800000, v35
	v_cmp_gt_f32_e32 vcc, s33, v35
	s_nop 1
	v_cndmask_b32_e32 v3, v35, v3, vcc
	v_rsq_f32_e32 v4, v3
	v_ashrrev_i32_e32 v3, 31, v2
	v_lshlrev_b64 v[2:3], 11, v[2:3]
	v_lshl_add_u64 v[36:37], v[98:99], 0, v[2:3]
	v_mul_f32_e32 v2, 0x45800000, v4
	v_cndmask_b32_e32 v40, v4, v2, vcc
	v_pk_mul_f32 v[2:3], v[30:31], v[40:41] op_sel_hi:[1,0]
	v_pk_mul_f32 v[4:5], v[32:33], v[40:41] op_sel_hi:[1,0]
	v_pk_mul_f32 v[26:27], v[26:27], v[40:41] op_sel_hi:[1,0]
	v_pk_mul_f32 v[28:29], v[28:29], v[40:41] op_sel_hi:[1,0]
	v_pk_mul_f32 v[4:5], v[116:117], v[4:5]
	v_pk_mul_f32 v[2:3], v[118:119], v[2:3]
	v_pk_mul_f32 v[28:29], v[112:113], v[28:29]
	v_pk_mul_f32 v[26:27], v[114:115], v[26:27]
	v_cvt_pk_bf16_f32 v2, v2, v3
	v_cvt_pk_bf16_f32 v3, v4, v5
	v_cvt_pk_bf16_f32 v4, v26, v27
	v_cvt_pk_bf16_f32 v5, v28, v29
	global_store_dwordx4 v[36:37], v[2:5], off
	v_cmp_gt_f32_e32 vcc, s33, v34
	v_pk_mul_f32 v[14:15], v[14:15], v[40:41] op_sel_hi:[1,0]
	v_pk_mul_f32 v[2:3], v[22:23], v[40:41] op_sel_hi:[1,0]
	v_pk_mul_f32 v[4:5], v[24:25], v[40:41] op_sel_hi:[1,0]
	v_pk_mul_f32 v[2:3], v[110:111], v[2:3]
	v_pk_mul_f32 v[4:5], v[108:109], v[4:5]
	v_cvt_pk_bf16_f32 v2, v2, v3
	v_cvt_pk_bf16_f32 v3, v4, v5
	v_mul_f32_e32 v4, 0x4b800000, v34
	v_cndmask_b32_e32 v4, v34, v4, vcc
	v_rsq_f32_e32 v22, v4
	v_pk_mul_f32 v[16:17], v[16:17], v[40:41] op_sel_hi:[1,0]
	v_pk_mul_f32 v[14:15], v[106:107], v[14:15]
	v_pk_mul_f32 v[16:17], v[104:105], v[16:17]
	v_cvt_pk_bf16_f32 v4, v14, v15
	v_cvt_pk_bf16_f32 v5, v16, v17
	global_store_dwordx4 v[36:37], v[2:5], off offset:64
	s_nop 1
	v_mul_f32_e32 v2, 0x45800000, v22
	v_cndmask_b32_e32 v14, v22, v2, vcc
	v_add_u32_e32 v2, s18, v146
	v_ashrrev_i32_e32 v3, 31, v2
	v_lshlrev_b64 v[2:3], 11, v[2:3]
	v_lshl_add_u64 v[16:17], v[98:99], 0, v[2:3]
	v_pk_mul_f32 v[2:3], v[18:19], v[14:15] op_sel_hi:[1,0]
	v_pk_mul_f32 v[4:5], v[20:21], v[14:15] op_sel_hi:[1,0]
	v_pk_mul_f32 v[10:11], v[10:11], v[14:15] op_sel_hi:[1,0]
	v_pk_mul_f32 v[12:13], v[12:13], v[14:15] op_sel_hi:[1,0]
	v_pk_mul_f32 v[4:5], v[116:117], v[4:5]
	v_pk_mul_f32 v[2:3], v[118:119], v[2:3]
	v_pk_mul_f32 v[12:13], v[112:113], v[12:13]
	v_pk_mul_f32 v[10:11], v[114:115], v[10:11]
	v_cvt_pk_bf16_f32 v2, v2, v3
	v_cvt_pk_bf16_f32 v3, v4, v5
	v_cvt_pk_bf16_f32 v4, v10, v11
	v_cvt_pk_bf16_f32 v5, v12, v13
	global_store_dwordx4 v[16:17], v[2:5], off
	s_andn2_b64 vcc, exec, s[66:67]
	s_mov_b64 s[18:19], -1
	v_pk_mul_f32 v[2:3], v[6:7], v[14:15] op_sel_hi:[1,0]
	v_pk_mul_f32 v[4:5], v[8:9], v[14:15] op_sel_hi:[1,0]
	v_pk_mul_f32 v[6:7], v[38:39], v[14:15] op_sel_hi:[1,0]
	v_pk_mul_f32 v[8:9], v[56:57], v[14:15] op_sel_hi:[1,0]
	v_pk_mul_f32 v[4:5], v[108:109], v[4:5]
	v_pk_mul_f32 v[2:3], v[110:111], v[2:3]
	v_pk_mul_f32 v[8:9], v[104:105], v[8:9]
	v_pk_mul_f32 v[6:7], v[106:107], v[6:7]
	v_cvt_pk_bf16_f32 v2, v2, v3
	v_cvt_pk_bf16_f32 v3, v4, v5
	v_cvt_pk_bf16_f32 v4, v6, v7
	v_cvt_pk_bf16_f32 v5, v8, v9
	global_store_dwordx4 v[16:17], v[2:5], off offset:64
	s_cbranch_vccnz .LBB0_341
	s_andn2_b64 vcc, exec, s[0:1]
	s_cbranch_vccnz .LBB0_340
	s_barrier
	s_branch .LBB0_340
